# swiglu epilogue regenerated with fewer VALU ops (rs folded into per-row constants, no hazard nops, shared store base), accumulator zeroing with v_mov_b64
# speedup vs baseline: 1.0106x; 1.0039x over previous
; template <class Epi, class Sched, bool ALIGN_EPI = false, bool SP2 = false>
; __device__ __forceinline__ void gemm_phase(PG8_LAS unsigned char* lds, const Gemm g, const Sched& S, const Epi& E) {
;     ...
; #pragma unroll
;         for (int a = 0; a < 2; ++a)
; #pragma unroll
;             for (int b = 0; b < 2; ++b)
; #pragma unroll
;                 for (int m = 0; m < 4; ++m)
; #pragma unroll
;                     for (int n = 0; n < 2; ++n) acc[a][b][m][n] = (f32x4){0.f, 0.f, 0.f, 0.f};
;         cur = nxt; cA = nA; cB = nB; ++ui;
.LBB0_505:
	s_add_u32 s31, s2, s45
	s_addc_u32 s36, s3, s44
	s_lshl_b32 s16, s80, 8
	v_add_u32_e32 v2, s16, v1
	v_ashrrev_i32_e32 v3, 31, v2
	v_add_u32_e32 v4, s16, v232
	s_lshl_b32 s16, s43, 10
	v_lshlrev_b64 v[2:3], 7, v[2:3]
	v_ashrrev_i32_e32 v5, 31, v4
	s_and_b32 s16, s16, 0x400
	v_lshlrev_b64 v[4:5], 7, v[4:5]
	s_waitcnt lgkmcnt(0)
	v_lshl_add_u64 v[130:131], v[196:197], 0, v[2:3]
	s_add_u32 s39, s14, 0x10000
	v_mov_b64_e32 v[2:3], 0
	v_add_u32_e32 v134, s16, v240
	v_lshl_add_u64 v[132:133], v[196:197], 0, v[4:5]
	v_add_u32_e32 v135, s16, v241
	s_addc_u32 s50, s15, 0
	s_mov_b64 s[14:15], 0
	v_mov_b64_e32 v[4:5], 0
	v_mov_b64_e32 v[10:11], 0
	v_mov_b64_e32 v[12:13], 0
	v_mov_b64_e32 v[18:19], 0
	v_mov_b64_e32 v[20:21], 0
	v_mov_b64_e32 v[26:27], 0
	v_mov_b64_e32 v[28:29], 0
	v_mov_b64_e32 v[34:35], 0
	v_mov_b64_e32 v[36:37], 0
	v_mov_b64_e32 v[42:43], 0
	v_mov_b64_e32 v[44:45], 0
	v_mov_b64_e32 v[50:51], 0
	v_mov_b64_e32 v[52:53], 0
	v_mov_b64_e32 v[58:59], 0
	v_mov_b64_e32 v[60:61], 0
	v_mov_b64_e32 v[6:7], 0
	v_mov_b64_e32 v[8:9], 0
	v_mov_b64_e32 v[14:15], 0
	v_mov_b64_e32 v[16:17], 0
	v_mov_b64_e32 v[22:23], 0
	v_mov_b64_e32 v[24:25], 0
	v_mov_b64_e32 v[30:31], 0
	v_mov_b64_e32 v[32:33], 0
	v_mov_b64_e32 v[38:39], 0
	v_mov_b64_e32 v[40:41], 0
	v_mov_b64_e32 v[46:47], 0
	v_mov_b64_e32 v[48:49], 0
	v_mov_b64_e32 v[54:55], 0
	v_mov_b64_e32 v[56:57], 0
	v_mov_b64_e32 v[62:63], 0
	v_mov_b64_e32 v[64:65], 0
	v_mov_b64_e32 v[66:67], 0
	v_mov_b64_e32 v[68:69], 0
	v_mov_b64_e32 v[74:75], 0
	v_mov_b64_e32 v[76:77], 0
	v_mov_b64_e32 v[82:83], 0
	v_mov_b64_e32 v[84:85], 0
	v_mov_b64_e32 v[90:91], 0
	v_mov_b64_e32 v[92:93], 0
	v_mov_b64_e32 v[98:99], 0
	v_mov_b64_e32 v[100:101], 0
	v_mov_b64_e32 v[106:107], 0
	v_mov_b64_e32 v[108:109], 0
	v_mov_b64_e32 v[114:115], 0
	v_mov_b64_e32 v[116:117], 0
	v_mov_b64_e32 v[122:123], 0
	v_mov_b64_e32 v[124:125], 0
	v_mov_b64_e32 v[70:71], 0
	v_mov_b64_e32 v[72:73], 0
	v_mov_b64_e32 v[78:79], 0
	v_mov_b64_e32 v[80:81], 0
	v_mov_b64_e32 v[86:87], 0
	v_mov_b64_e32 v[88:89], 0
	v_mov_b64_e32 v[94:95], 0
	v_mov_b64_e32 v[96:97], 0
	v_mov_b64_e32 v[102:103], 0
	v_mov_b64_e32 v[104:105], 0
	v_mov_b64_e32 v[110:111], 0
	v_mov_b64_e32 v[112:113], 0
	v_mov_b64_e32 v[118:119], 0
	v_mov_b64_e32 v[120:121], 0
	v_mov_b64_e32 v[126:127], 0
	v_mov_b64_e32 v[128:129], 0
	s_branch .LBB0_508

; #define LAS __attribute__((address_space(3)))
; __device__ __forceinline__ unsigned pk2(float lo, float hi) { f32x2 v = {lo, hi}; bf16x2_t b = __builtin_convertvector(v, bf16x2_t); return __builtin_bit_cast(unsigned, b); }
; __device__ __forceinline__ void epi_swiglu(bf16_t* H, const LAS float* tbl, const f32x4 (&acc)[2][2][4][2], const Unit& u, int wr, int wc, int fr, int fq) {
;     const int col0 = u.pn * 128 + wc * 32 + fq * 8;
; #pragma unroll
;     for (int it = 0; it < 8; ++it) {
;         const int ai = it >> 2, m = it & 3; const int r = opaque(EPI_ROW(it));
;         const float rs = tbl[EPI_LROW(it)];
;         u32x4 w;
; #pragma unroll
;         for (int n = 0; n < 2; ++n) {
;             const f32x4 g = acc[ai][0][m][n] * rs, up = acc[ai][1][m][n] * rs; float hv[4];
; #pragma unroll
;             for (int i = 0; i < 4; ++i) hv[i] = g[i] * __builtin_amdgcn_rcpf(1.0f + __expf(-g[i])) * up[i];
;             w[2 * n] = pk2(hv[0], hv[1]); w[2 * n + 1] = pk2(hv[2], hv[3]);
;         }
;         *(u32x4*)(H + ((size_t)(r >> 8) * (DFF / 64) + (col0 >> 6)) * 16384 + (r & 255) * 64 + (col0 & 63)) = w;
;     }
.LBB0_752:
	s_and_b64 vcc, exec, s[2:3]
	s_cbranch_vccz .LBB0_754
	s_mov_b64 s[2:3], s[96:97]
	s_add_u32 s2, s2, 0x17e00000
	s_addc_u32 s3, s3, 0
	s_lshl_b32 s12, s77, 7
	v_readlane_b32 s13, v255, 1
	s_or_b32 s12, s12, s13
	v_readlane_b32 s13, v254, 31
	s_lshl_b32 s13, s13, 2
	s_add_i32 s39, s39, s13
	s_lshl_b32 s14, s81, 8
	s_waitcnt lgkmcnt(0)
	v_add_u32_e32 v131, s14, v193
	v_lshl_add_u32 v130, v183, 2, s39
	ds_read_b32 v140, v130
	ds_read_b32 v141, v130 offset:64
	ds_read_b32 v142, v130 offset:128
	ds_read_b32 v143, v130 offset:192
	ds_read_b32 v144, v130 offset:512
	ds_read_b32 v145, v130 offset:576
	ds_read_b32 v146, v130 offset:640
	ds_read_b32 v147, v130 offset:704
	s_ashr_i32 s12, s12, 6
	s_ashr_i32 s13, s12, 31
	v_mov_b32_e32 v199, v0
	v_lshrrev_b32_e32 v132, 8, v131
	v_mul_i32_i24_e32 v132, 0x58, v132
	v_ashrrev_i32_e32 v133, 31, v132
	v_lshl_add_u64 v[132:133], v[132:133], 0, s[12:13]
	v_lshlrev_b64 v[132:133], 15, v[132:133]
	v_lshl_add_u64 v[132:133], s[2:3], 0, v[132:133]
	v_lshlrev_b32_e32 v134, 7, v131
	v_and_b32_e32 v134, 0x7f80, v134
	v_mov_b32_e32 v135, v0
	v_lshl_add_u64 v[132:133], v[132:133], 0, v[134:135]
	v_lshl_add_u64 v[132:133], v[132:133], 0, v[198:199]
	s_mov_b64 s[12:13], 0x1000
	s_mov_b64 s[14:15], 0x5000
	v_lshl_add_u64 v[134:135], v[132:133], 0, s[12:13]
	v_lshl_add_u64 v[136:137], v[132:133], 0, s[14:15]
	v_mov_b32_e32 v138, 1.0
	v_mov_b32_e32 v139, 1.0
	s_waitcnt lgkmcnt(0)
	v_mul_f32_e32 v148, 0xbfb8aa3b, v140
	v_mul_f32_e32 v150, v140, v140
	v_pk_mul_f32 v[152:153], v[126:127], v[148:149] op_sel_hi:[1,0]
	v_pk_mul_f32 v[154:155], v[128:129], v[148:149] op_sel_hi:[1,0]
	v_pk_mul_f32 v[156:157], v[118:119], v[148:149] op_sel_hi:[1,0]
	v_pk_mul_f32 v[158:159], v[120:121], v[148:149] op_sel_hi:[1,0]
	v_exp_f32_e32 v152, v152
	v_exp_f32_e32 v153, v153
	v_exp_f32_e32 v154, v154
	v_exp_f32_e32 v155, v155
	v_exp_f32_e32 v156, v156
	v_exp_f32_e32 v157, v157
	v_exp_f32_e32 v158, v158
	v_exp_f32_e32 v159, v159
	v_pk_mul_f32 v[126:127], v[126:127], v[122:123]
	v_pk_mul_f32 v[128:129], v[128:129], v[124:125]
	v_pk_mul_f32 v[118:119], v[118:119], v[114:115]
	v_pk_mul_f32 v[120:121], v[120:121], v[116:117]
	v_pk_add_f32 v[152:153], v[152:153], v[138:139]
	v_pk_add_f32 v[154:155], v[154:155], v[138:139]
	v_pk_add_f32 v[156:157], v[156:157], v[138:139]
	v_pk_add_f32 v[158:159], v[158:159], v[138:139]
	v_rcp_f32_e32 v152, v152
	v_rcp_f32_e32 v153, v153
	v_rcp_f32_e32 v154, v154
	v_rcp_f32_e32 v155, v155
	v_rcp_f32_e32 v156, v156
	v_rcp_f32_e32 v157, v157
	v_rcp_f32_e32 v158, v158
	v_rcp_f32_e32 v159, v159
	v_pk_mul_f32 v[126:127], v[126:127], v[150:151] op_sel_hi:[1,0]
	v_pk_mul_f32 v[128:129], v[128:129], v[150:151] op_sel_hi:[1,0]
	v_pk_mul_f32 v[118:119], v[118:119], v[150:151] op_sel_hi:[1,0]
	v_pk_mul_f32 v[120:121], v[120:121], v[150:151] op_sel_hi:[1,0]
	v_pk_mul_f32 v[126:127], v[126:127], v[152:153]
	v_pk_mul_f32 v[128:129], v[128:129], v[154:155]
	v_pk_mul_f32 v[118:119], v[118:119], v[156:157]
	v_pk_mul_f32 v[120:121], v[120:121], v[158:159]
	v_cvt_pk_bf16_f32 v160, v126, v127
	v_cvt_pk_bf16_f32 v161, v128, v129
	v_cvt_pk_bf16_f32 v162, v118, v119
	v_cvt_pk_bf16_f32 v163, v120, v121
	global_store_dwordx4 v[134:135], v[160:163], off offset:-4096
	v_mul_f32_e32 v148, 0xbfb8aa3b, v141
	v_mul_f32_e32 v150, v141, v141
	v_pk_mul_f32 v[152:153], v[110:111], v[148:149] op_sel_hi:[1,0]
	v_pk_mul_f32 v[154:155], v[112:113], v[148:149] op_sel_hi:[1,0]
	v_pk_mul_f32 v[156:157], v[102:103], v[148:149] op_sel_hi:[1,0]
	v_pk_mul_f32 v[158:159], v[104:105], v[148:149] op_sel_hi:[1,0]
	v_exp_f32_e32 v152, v152
	v_exp_f32_e32 v153, v153
	v_exp_f32_e32 v154, v154
	v_exp_f32_e32 v155, v155
	v_exp_f32_e32 v156, v156
	v_exp_f32_e32 v157, v157
	v_exp_f32_e32 v158, v158
	v_exp_f32_e32 v159, v159
	v_pk_mul_f32 v[110:111], v[110:111], v[106:107]
	v_pk_mul_f32 v[112:113], v[112:113], v[108:109]
	v_pk_mul_f32 v[102:103], v[102:103], v[98:99]
	v_pk_mul_f32 v[104:105], v[104:105], v[100:101]
	v_pk_add_f32 v[152:153], v[152:153], v[138:139]
	v_pk_add_f32 v[154:155], v[154:155], v[138:139]
	v_pk_add_f32 v[156:157], v[156:157], v[138:139]
	v_pk_add_f32 v[158:159], v[158:159], v[138:139]
	v_rcp_f32_e32 v152, v152
	v_rcp_f32_e32 v153, v153
	v_rcp_f32_e32 v154, v154
	v_rcp_f32_e32 v155, v155
	v_rcp_f32_e32 v156, v156
	v_rcp_f32_e32 v157, v157
	v_rcp_f32_e32 v158, v158
	v_rcp_f32_e32 v159, v159
	v_pk_mul_f32 v[110:111], v[110:111], v[150:151] op_sel_hi:[1,0]
	v_pk_mul_f32 v[112:113], v[112:113], v[150:151] op_sel_hi:[1,0]
	v_pk_mul_f32 v[102:103], v[102:103], v[150:151] op_sel_hi:[1,0]
	v_pk_mul_f32 v[104:105], v[104:105], v[150:151] op_sel_hi:[1,0]
	v_pk_mul_f32 v[110:111], v[110:111], v[152:153]
	v_pk_mul_f32 v[112:113], v[112:113], v[154:155]
	v_pk_mul_f32 v[102:103], v[102:103], v[156:157]
	v_pk_mul_f32 v[104:105], v[104:105], v[158:159]
	v_cvt_pk_bf16_f32 v164, v110, v111
	v_cvt_pk_bf16_f32 v165, v112, v113
	v_cvt_pk_bf16_f32 v166, v102, v103
	v_cvt_pk_bf16_f32 v167, v104, v105
	global_store_dwordx4 v[134:135], v[164:167], off offset:-2048
	v_mul_f32_e32 v148, 0xbfb8aa3b, v142
	v_mul_f32_e32 v150, v142, v142
	v_pk_mul_f32 v[152:153], v[94:95], v[148:149] op_sel_hi:[1,0]
	v_pk_mul_f32 v[154:155], v[96:97], v[148:149] op_sel_hi:[1,0]
	v_pk_mul_f32 v[156:157], v[86:87], v[148:149] op_sel_hi:[1,0]
	v_pk_mul_f32 v[158:159], v[88:89], v[148:149] op_sel_hi:[1,0]
	v_exp_f32_e32 v152, v152
	v_exp_f32_e32 v153, v153
	v_exp_f32_e32 v154, v154
	v_exp_f32_e32 v155, v155
	v_exp_f32_e32 v156, v156
	v_exp_f32_e32 v157, v157
	v_exp_f32_e32 v158, v158
	v_exp_f32_e32 v159, v159
	v_pk_mul_f32 v[94:95], v[94:95], v[90:91]
	v_pk_mul_f32 v[96:97], v[96:97], v[92:93]
; __device__ __forceinline__ unsigned pk2(float lo, float hi) { f32x2 v = {lo, hi}; bf16x2_t b = __builtin_convertvector(v, bf16x2_t); return __builtin_bit_cast(unsigned, b); }
; __device__ __forceinline__ void epi_swiglu(bf16_t* H, const LAS float* tbl, const f32x4 (&acc)[2][2][4][2], const Unit& u, int wr, int wc, int fr, int fq) {
;     ...
;     for (int it = 0; it < 8; ++it) {
;         const int ai = it >> 2, m = it & 3; const int r = opaque(EPI_ROW(it));
;         const float rs = tbl[EPI_LROW(it)];
;         u32x4 w;
; #pragma unroll
;         for (int n = 0; n < 2; ++n) {
;             const f32x4 g = acc[ai][0][m][n] * rs, up = acc[ai][1][m][n] * rs; float hv[4];
; #pragma unroll
;             for (int i = 0; i < 4; ++i) hv[i] = g[i] * __builtin_amdgcn_rcpf(1.0f + __expf(-g[i])) * up[i];
;             w[2 * n] = pk2(hv[0], hv[1]); w[2 * n + 1] = pk2(hv[2], hv[3]);
;         }
;         *(u32x4*)(H + ((size_t)(r >> 8) * (DFF / 64) + (col0 >> 6)) * 16384 + (r & 255) * 64 + (col0 & 63)) = w;
;     }
	v_pk_mul_f32 v[86:87], v[86:87], v[82:83]
	v_pk_mul_f32 v[88:89], v[88:89], v[84:85]
	v_pk_add_f32 v[152:153], v[152:153], v[138:139]
	v_pk_add_f32 v[154:155], v[154:155], v[138:139]
	v_pk_add_f32 v[156:157], v[156:157], v[138:139]
	v_pk_add_f32 v[158:159], v[158:159], v[138:139]
	v_rcp_f32_e32 v152, v152
	v_rcp_f32_e32 v153, v153
	v_rcp_f32_e32 v154, v154
	v_rcp_f32_e32 v155, v155
	v_rcp_f32_e32 v156, v156
	v_rcp_f32_e32 v157, v157
	v_rcp_f32_e32 v158, v158
	v_rcp_f32_e32 v159, v159
	v_pk_mul_f32 v[94:95], v[94:95], v[150:151] op_sel_hi:[1,0]
	v_pk_mul_f32 v[96:97], v[96:97], v[150:151] op_sel_hi:[1,0]
	v_pk_mul_f32 v[86:87], v[86:87], v[150:151] op_sel_hi:[1,0]
	v_pk_mul_f32 v[88:89], v[88:89], v[150:151] op_sel_hi:[1,0]
	v_pk_mul_f32 v[94:95], v[94:95], v[152:153]
	v_pk_mul_f32 v[96:97], v[96:97], v[154:155]
	v_pk_mul_f32 v[86:87], v[86:87], v[156:157]
	v_pk_mul_f32 v[88:89], v[88:89], v[158:159]
	v_cvt_pk_bf16_f32 v160, v94, v95
	v_cvt_pk_bf16_f32 v161, v96, v97
	v_cvt_pk_bf16_f32 v162, v86, v87
	v_cvt_pk_bf16_f32 v163, v88, v89
	global_store_dwordx4 v[134:135], v[160:163], off
	v_mul_f32_e32 v148, 0xbfb8aa3b, v143
	v_mul_f32_e32 v150, v143, v143
	v_pk_mul_f32 v[152:153], v[78:79], v[148:149] op_sel_hi:[1,0]
	v_pk_mul_f32 v[154:155], v[80:81], v[148:149] op_sel_hi:[1,0]
	v_pk_mul_f32 v[156:157], v[70:71], v[148:149] op_sel_hi:[1,0]
	v_pk_mul_f32 v[158:159], v[72:73], v[148:149] op_sel_hi:[1,0]
	v_exp_f32_e32 v152, v152
	v_exp_f32_e32 v153, v153
	v_exp_f32_e32 v154, v154
	v_exp_f32_e32 v155, v155
	v_exp_f32_e32 v156, v156
	v_exp_f32_e32 v157, v157
	v_exp_f32_e32 v158, v158
	v_exp_f32_e32 v159, v159
	v_pk_mul_f32 v[78:79], v[78:79], v[74:75]
	v_pk_mul_f32 v[80:81], v[80:81], v[76:77]
	v_pk_mul_f32 v[70:71], v[70:71], v[66:67]
	v_pk_mul_f32 v[72:73], v[72:73], v[68:69]
	v_pk_add_f32 v[152:153], v[152:153], v[138:139]
	v_pk_add_f32 v[154:155], v[154:155], v[138:139]
	v_pk_add_f32 v[156:157], v[156:157], v[138:139]
	v_pk_add_f32 v[158:159], v[158:159], v[138:139]
	v_rcp_f32_e32 v152, v152
	v_rcp_f32_e32 v153, v153
	v_rcp_f32_e32 v154, v154
	v_rcp_f32_e32 v155, v155
	v_rcp_f32_e32 v156, v156
	v_rcp_f32_e32 v157, v157
	v_rcp_f32_e32 v158, v158
	v_rcp_f32_e32 v159, v159
	v_pk_mul_f32 v[78:79], v[78:79], v[150:151] op_sel_hi:[1,0]
	v_pk_mul_f32 v[80:81], v[80:81], v[150:151] op_sel_hi:[1,0]
	v_pk_mul_f32 v[70:71], v[70:71], v[150:151] op_sel_hi:[1,0]
	v_pk_mul_f32 v[72:73], v[72:73], v[150:151] op_sel_hi:[1,0]
	v_pk_mul_f32 v[78:79], v[78:79], v[152:153]
	v_pk_mul_f32 v[80:81], v[80:81], v[154:155]
	v_pk_mul_f32 v[70:71], v[70:71], v[156:157]
	v_pk_mul_f32 v[72:73], v[72:73], v[158:159]
	v_cvt_pk_bf16_f32 v164, v78, v79
	v_cvt_pk_bf16_f32 v165, v80, v81
	v_cvt_pk_bf16_f32 v166, v70, v71
	v_cvt_pk_bf16_f32 v167, v72, v73
	global_store_dwordx4 v[134:135], v[164:167], off offset:2048
	v_mul_f32_e32 v148, 0xbfb8aa3b, v144
	v_mul_f32_e32 v150, v144, v144
	v_pk_mul_f32 v[152:153], v[62:63], v[148:149] op_sel_hi:[1,0]
	v_pk_mul_f32 v[154:155], v[64:65], v[148:149] op_sel_hi:[1,0]
	v_pk_mul_f32 v[156:157], v[54:55], v[148:149] op_sel_hi:[1,0]
	v_pk_mul_f32 v[158:159], v[56:57], v[148:149] op_sel_hi:[1,0]
	v_exp_f32_e32 v152, v152
	v_exp_f32_e32 v153, v153
	v_exp_f32_e32 v154, v154
	v_exp_f32_e32 v155, v155
	v_exp_f32_e32 v156, v156
	v_exp_f32_e32 v157, v157
	v_exp_f32_e32 v158, v158
	v_exp_f32_e32 v159, v159
	v_pk_mul_f32 v[62:63], v[62:63], v[58:59]
	v_pk_mul_f32 v[64:65], v[64:65], v[60:61]
	v_pk_mul_f32 v[54:55], v[54:55], v[50:51]
	v_pk_mul_f32 v[56:57], v[56:57], v[52:53]
	v_pk_add_f32 v[152:153], v[152:153], v[138:139]
	v_pk_add_f32 v[154:155], v[154:155], v[138:139]
	v_pk_add_f32 v[156:157], v[156:157], v[138:139]
	v_pk_add_f32 v[158:159], v[158:159], v[138:139]
	v_rcp_f32_e32 v152, v152
	v_rcp_f32_e32 v153, v153
	v_rcp_f32_e32 v154, v154
	v_rcp_f32_e32 v155, v155
	v_rcp_f32_e32 v156, v156
	v_rcp_f32_e32 v157, v157
	v_rcp_f32_e32 v158, v158
	v_rcp_f32_e32 v159, v159
	v_pk_mul_f32 v[62:63], v[62:63], v[150:151] op_sel_hi:[1,0]
	v_pk_mul_f32 v[64:65], v[64:65], v[150:151] op_sel_hi:[1,0]
	v_pk_mul_f32 v[54:55], v[54:55], v[150:151] op_sel_hi:[1,0]
	v_pk_mul_f32 v[56:57], v[56:57], v[150:151] op_sel_hi:[1,0]
	v_pk_mul_f32 v[62:63], v[62:63], v[152:153]
	v_pk_mul_f32 v[64:65], v[64:65], v[154:155]
	v_pk_mul_f32 v[54:55], v[54:55], v[156:157]
	v_pk_mul_f32 v[56:57], v[56:57], v[158:159]
	v_cvt_pk_bf16_f32 v160, v62, v63
	v_cvt_pk_bf16_f32 v161, v64, v65
	v_cvt_pk_bf16_f32 v162, v54, v55
	v_cvt_pk_bf16_f32 v163, v56, v57
	global_store_dwordx4 v[136:137], v[160:163], off offset:-4096
	v_mul_f32_e32 v148, 0xbfb8aa3b, v145
	v_mul_f32_e32 v150, v145, v145
	v_pk_mul_f32 v[152:153], v[46:47], v[148:149] op_sel_hi:[1,0]
	v_pk_mul_f32 v[154:155], v[48:49], v[148:149] op_sel_hi:[1,0]
	v_pk_mul_f32 v[156:157], v[38:39], v[148:149] op_sel_hi:[1,0]
; __device__ __forceinline__ unsigned pk2(float lo, float hi) { f32x2 v = {lo, hi}; bf16x2_t b = __builtin_convertvector(v, bf16x2_t); return __builtin_bit_cast(unsigned, b); }
; __device__ __forceinline__ void epi_swiglu(bf16_t* H, const LAS float* tbl, const f32x4 (&acc)[2][2][4][2], const Unit& u, int wr, int wc, int fr, int fq) {
;     ...
;     for (int it = 0; it < 8; ++it) {
;         const int ai = it >> 2, m = it & 3; const int r = opaque(EPI_ROW(it));
;         const float rs = tbl[EPI_LROW(it)];
;         u32x4 w;
; #pragma unroll
;         for (int n = 0; n < 2; ++n) {
;             const f32x4 g = acc[ai][0][m][n] * rs, up = acc[ai][1][m][n] * rs; float hv[4];
; #pragma unroll
;             for (int i = 0; i < 4; ++i) hv[i] = g[i] * __builtin_amdgcn_rcpf(1.0f + __expf(-g[i])) * up[i];
;             w[2 * n] = pk2(hv[0], hv[1]); w[2 * n + 1] = pk2(hv[2], hv[3]);
;         }
;         *(u32x4*)(H + ((size_t)(r >> 8) * (DFF / 64) + (col0 >> 6)) * 16384 + (r & 255) * 64 + (col0 & 63)) = w;
;     }
	v_pk_mul_f32 v[158:159], v[40:41], v[148:149] op_sel_hi:[1,0]
	v_exp_f32_e32 v152, v152
	v_exp_f32_e32 v153, v153
	v_exp_f32_e32 v154, v154
	v_exp_f32_e32 v155, v155
	v_exp_f32_e32 v156, v156
	v_exp_f32_e32 v157, v157
	v_exp_f32_e32 v158, v158
	v_exp_f32_e32 v159, v159
	v_pk_mul_f32 v[46:47], v[46:47], v[42:43]
	v_pk_mul_f32 v[48:49], v[48:49], v[44:45]
	v_pk_mul_f32 v[38:39], v[38:39], v[34:35]
	v_pk_mul_f32 v[40:41], v[40:41], v[36:37]
	v_pk_add_f32 v[152:153], v[152:153], v[138:139]
	v_pk_add_f32 v[154:155], v[154:155], v[138:139]
	v_pk_add_f32 v[156:157], v[156:157], v[138:139]
	v_pk_add_f32 v[158:159], v[158:159], v[138:139]
	v_rcp_f32_e32 v152, v152
	v_rcp_f32_e32 v153, v153
	v_rcp_f32_e32 v154, v154
	v_rcp_f32_e32 v155, v155
	v_rcp_f32_e32 v156, v156
	v_rcp_f32_e32 v157, v157
	v_rcp_f32_e32 v158, v158
	v_rcp_f32_e32 v159, v159
	v_pk_mul_f32 v[46:47], v[46:47], v[150:151] op_sel_hi:[1,0]
	v_pk_mul_f32 v[48:49], v[48:49], v[150:151] op_sel_hi:[1,0]
	v_pk_mul_f32 v[38:39], v[38:39], v[150:151] op_sel_hi:[1,0]
	v_pk_mul_f32 v[40:41], v[40:41], v[150:151] op_sel_hi:[1,0]
	v_pk_mul_f32 v[46:47], v[46:47], v[152:153]
	v_pk_mul_f32 v[48:49], v[48:49], v[154:155]
	v_pk_mul_f32 v[38:39], v[38:39], v[156:157]
	v_pk_mul_f32 v[40:41], v[40:41], v[158:159]
	v_cvt_pk_bf16_f32 v164, v46, v47
	v_cvt_pk_bf16_f32 v165, v48, v49
	v_cvt_pk_bf16_f32 v166, v38, v39
	v_cvt_pk_bf16_f32 v167, v40, v41
	global_store_dwordx4 v[136:137], v[164:167], off offset:-2048
	v_mul_f32_e32 v148, 0xbfb8aa3b, v146
	v_mul_f32_e32 v150, v146, v146
	v_pk_mul_f32 v[152:153], v[30:31], v[148:149] op_sel_hi:[1,0]
	v_pk_mul_f32 v[154:155], v[32:33], v[148:149] op_sel_hi:[1,0]
	v_pk_mul_f32 v[156:157], v[22:23], v[148:149] op_sel_hi:[1,0]
	v_pk_mul_f32 v[158:159], v[24:25], v[148:149] op_sel_hi:[1,0]
	v_exp_f32_e32 v152, v152
	v_exp_f32_e32 v153, v153
	v_exp_f32_e32 v154, v154
	v_exp_f32_e32 v155, v155
	v_exp_f32_e32 v156, v156
	v_exp_f32_e32 v157, v157
	v_exp_f32_e32 v158, v158
	v_exp_f32_e32 v159, v159
	v_pk_mul_f32 v[30:31], v[30:31], v[26:27]
	v_pk_mul_f32 v[32:33], v[32:33], v[28:29]
	v_pk_mul_f32 v[22:23], v[22:23], v[18:19]
	v_pk_mul_f32 v[24:25], v[24:25], v[20:21]
	v_pk_add_f32 v[152:153], v[152:153], v[138:139]
	v_pk_add_f32 v[154:155], v[154:155], v[138:139]
	v_pk_add_f32 v[156:157], v[156:157], v[138:139]
	v_pk_add_f32 v[158:159], v[158:159], v[138:139]
	v_rcp_f32_e32 v152, v152
	v_rcp_f32_e32 v153, v153
	v_rcp_f32_e32 v154, v154
	v_rcp_f32_e32 v155, v155
	v_rcp_f32_e32 v156, v156
	v_rcp_f32_e32 v157, v157
	v_rcp_f32_e32 v158, v158
	v_rcp_f32_e32 v159, v159
	v_pk_mul_f32 v[30:31], v[30:31], v[150:151] op_sel_hi:[1,0]
	v_pk_mul_f32 v[32:33], v[32:33], v[150:151] op_sel_hi:[1,0]
	v_pk_mul_f32 v[22:23], v[22:23], v[150:151] op_sel_hi:[1,0]
	v_pk_mul_f32 v[24:25], v[24:25], v[150:151] op_sel_hi:[1,0]
	v_pk_mul_f32 v[30:31], v[30:31], v[152:153]
	v_pk_mul_f32 v[32:33], v[32:33], v[154:155]
	v_pk_mul_f32 v[22:23], v[22:23], v[156:157]
	v_pk_mul_f32 v[24:25], v[24:25], v[158:159]
	v_cvt_pk_bf16_f32 v160, v30, v31
	v_cvt_pk_bf16_f32 v161, v32, v33
	v_cvt_pk_bf16_f32 v162, v22, v23
	v_cvt_pk_bf16_f32 v163, v24, v25
	global_store_dwordx4 v[136:137], v[160:163], off
	v_mul_f32_e32 v148, 0xbfb8aa3b, v147
	v_mul_f32_e32 v150, v147, v147
	v_pk_mul_f32 v[152:153], v[14:15], v[148:149] op_sel_hi:[1,0]
	v_pk_mul_f32 v[154:155], v[16:17], v[148:149] op_sel_hi:[1,0]
	v_pk_mul_f32 v[156:157], v[6:7], v[148:149] op_sel_hi:[1,0]
	v_pk_mul_f32 v[158:159], v[8:9], v[148:149] op_sel_hi:[1,0]
	v_exp_f32_e32 v152, v152
	v_exp_f32_e32 v153, v153
	v_exp_f32_e32 v154, v154
	v_exp_f32_e32 v155, v155
	v_exp_f32_e32 v156, v156
	v_exp_f32_e32 v157, v157
	v_exp_f32_e32 v158, v158
	v_exp_f32_e32 v159, v159
	v_pk_mul_f32 v[14:15], v[14:15], v[10:11]
	v_pk_mul_f32 v[16:17], v[16:17], v[12:13]
	v_pk_mul_f32 v[6:7], v[6:7], v[2:3]
	v_pk_mul_f32 v[8:9], v[8:9], v[4:5]
	v_pk_add_f32 v[152:153], v[152:153], v[138:139]
	v_pk_add_f32 v[154:155], v[154:155], v[138:139]
	v_pk_add_f32 v[156:157], v[156:157], v[138:139]
	v_pk_add_f32 v[158:159], v[158:159], v[138:139]
	v_rcp_f32_e32 v152, v152
	v_rcp_f32_e32 v153, v153
	v_rcp_f32_e32 v154, v154
	v_rcp_f32_e32 v155, v155
	v_rcp_f32_e32 v156, v156
	v_rcp_f32_e32 v157, v157
	v_rcp_f32_e32 v158, v158
	v_rcp_f32_e32 v159, v159
	v_pk_mul_f32 v[14:15], v[14:15], v[150:151] op_sel_hi:[1,0]
	v_pk_mul_f32 v[16:17], v[16:17], v[150:151] op_sel_hi:[1,0]
	v_pk_mul_f32 v[6:7], v[6:7], v[150:151] op_sel_hi:[1,0]
	v_pk_mul_f32 v[8:9], v[8:9], v[150:151] op_sel_hi:[1,0]
	v_pk_mul_f32 v[14:15], v[14:15], v[152:153]
	v_pk_mul_f32 v[16:17], v[16:17], v[154:155]
	v_pk_mul_f32 v[6:7], v[6:7], v[156:157]
	v_pk_mul_f32 v[8:9], v[8:9], v[158:159]
	v_cvt_pk_bf16_f32 v164, v14, v15
	v_cvt_pk_bf16_f32 v165, v16, v17
	v_cvt_pk_bf16_f32 v166, v6, v7
	v_cvt_pk_bf16_f32 v167, v8, v9
	global_store_dwordx4 v[136:137], v[164:167], off offset:2048
